# stack: HG stagger + SSD half-offset + final-norm nt + EpiRes ssq partials consolidated through LDS (one 16B store per row)
# baseline (speedup 1.0000x reference)
; __device__ __forceinline__ unsigned pk2(float lo, float hi) { f32x2n v = {lo, hi}; bf16x2n b = __builtin_convertvector(v, bf16x2n); return __builtin_bit_cast(unsigned, b); }
;     __device__ __forceinline__ void operator()(const f32x4 (&acc)[2][2][4][2], const Unit& u, int wr, int wc, int fr, int fq) const {
;     ...
;             for (int m = 0; m < 4; ++m) { const unsigned row = row0 + ai * HALF + m * 16; const unsigned off = row * 1024u + col0; float s = 0.f;
;                 const u32x4 bv0 = *(const u32x4*)(xb + off), bv1 = *(const u32x4*)(xb + off + HALF);
; #pragma unroll
;                 for (int bj = 0; bj < 2; ++bj) { const u32x4 bv = bj ? bv1 : bv0;
;                     const f32x4 b0 = {__uint_as_float(bv.x << 16), __uint_as_float(bv.x & 0xffff0000u), __uint_as_float(bv.y << 16), __uint_as_float(bv.y & 0xffff0000u)};
;                     const f32x4 b1 = {__uint_as_float(bv.z << 16), __uint_as_float(bv.z & 0xffff0000u), __uint_as_float(bv.w << 16), __uint_as_float(bv.w & 0xffff0000u)};
;                     const f32x4 v0 = b0 + acc[ai][bj][m][0] * scale, v1 = b1 + acc[ai][bj][m][1] * scale;
;                     u32x4 w; w.x = pk2(v0[0], v0[1]); w.y = pk2(v0[2], v0[3]); w.z = pk2(v1[0], v1[1]); w.w = pk2(v1[2], v1[3]);
;                     *(u32x4*)(xb + off + bj * HALF) = w;
;                     s += (v0[0] * v0[0] + v0[1] * v0[1]) + (v0[2] * v0[2] + v0[3] * v0[3]) + (v1[0] * v1[0] + v1[1] * v1[1]) + (v1[2] * v1[2] + v1[3] * v1[3]); }
.LBB0_667:
	v_lshl_add_u32 v146, s96, 8, v9
	v_lshl_or_b32 v155, s56, 8, v151
	v_lshlrev_b32_e32 v147, 6, v146
	v_lshl_add_u32 v146, v146, 10, v155
	v_lshlrev_b32_e32 v146, 1, v146
	s_mov_b64 s[40:41], s[62:63]
	global_load_dwordx4 v[178:181], v146, s[40:41]
	global_load_dwordx4 v[182:185], v146, s[40:41] offset:256
	s_add_u32 s40, s62, 0x8000
	s_addc_u32 s41, s63, 0
	global_load_dwordx4 v[186:189], v146, s[40:41]
	global_load_dwordx4 v[190:193], v146, s[40:41] offset:256
	s_add_u32 s40, s62, 0x10000
	s_addc_u32 s41, s63, 0
	global_load_dwordx4 v[210:213], v146, s[40:41]
	global_load_dwordx4 v[214:217], v146, s[40:41] offset:256
	s_add_u32 s40, s62, 0x18000
	s_addc_u32 s41, s63, 0
	global_load_dwordx4 v[218:221], v146, s[40:41]
	global_load_dwordx4 v[222:225], v146, s[40:41] offset:256
	s_add_u32 s40, s62, 0x40000
	s_addc_u32 s41, s63, 0
	global_load_dwordx4 v[226:229], v146, s[40:41]
	global_load_dwordx4 v[230:233], v146, s[40:41] offset:256
	s_add_u32 s40, s62, 0x48000
	s_addc_u32 s41, s63, 0
	global_load_dwordx4 v[234:237], v146, s[40:41]
	global_load_dwordx4 v[238:241], v146, s[40:41] offset:256
	s_add_u32 s40, s62, 0x50000
	s_addc_u32 s41, s63, 0
	global_load_dwordx4 v[242:245], v146, s[40:41]
	global_load_dwordx4 v[246:249], v146, s[40:41] offset:256
	s_add_u32 s40, s62, 0x58000
	s_addc_u32 s41, s63, 0
	global_load_dwordx4 v[170:173], v146, s[40:41]
	global_load_dwordx4 v[174:177], v146, s[40:41] offset:256
	v_xor_b32_e32 v153, 16, v202
	v_xor_b32_e32 v139, 32, v202
	v_lshlrev_b32_e32 v153, 2, v153
	v_lshlrev_b32_e32 v139, 2, v139
	s_waitcnt vmcnt(14)
	s_mov_b64 s[40:41], s[62:63]
	v_lshlrev_b32_e32 v148, 16, v178
	v_and_b32_e32 v149, 0xffff0000, v178
	v_lshlrev_b32_e32 v154, 16, v179
	v_and_b32_e32 v155, 0xffff0000, v179
	v_lshlrev_b32_e32 v156, 16, v180
	v_and_b32_e32 v157, 0xffff0000, v180
	v_lshlrev_b32_e32 v194, 16, v181
	v_and_b32_e32 v195, 0xffff0000, v181
	v_pk_fma_f32 v[126:127], v[140:141], v[126:127], v[148:149]
	v_pk_fma_f32 v[128:129], v[140:141], v[128:129], v[154:155]
	v_pk_fma_f32 v[122:123], v[140:141], v[122:123], v[156:157]
	v_pk_fma_f32 v[124:125], v[140:141], v[124:125], v[194:195]
	v_cvt_pk_bf16_f32 v196, v126, v127
	v_cvt_pk_bf16_f32 v197, v128, v129
	v_cvt_pk_bf16_f32 v198, v122, v123
	v_cvt_pk_bf16_f32 v199, v124, v125
	global_store_dwordx4 v146, v[196:199], s[40:41]
	v_pk_mul_f32 v[178:179], v[126:127], v[126:127]
	v_pk_fma_f32 v[178:179], v[128:129], v[128:129], v[178:179]
	v_pk_fma_f32 v[178:179], v[122:123], v[122:123], v[178:179]
	v_pk_fma_f32 v[178:179], v[124:125], v[124:125], v[178:179]
	v_lshlrev_b32_e32 v148, 16, v182
	v_and_b32_e32 v149, 0xffff0000, v182
	v_lshlrev_b32_e32 v154, 16, v183
	v_and_b32_e32 v155, 0xffff0000, v183
	v_lshlrev_b32_e32 v156, 16, v184
	v_and_b32_e32 v157, 0xffff0000, v184
	v_lshlrev_b32_e32 v194, 16, v185
	v_and_b32_e32 v195, 0xffff0000, v185
	v_pk_fma_f32 v[118:119], v[140:141], v[118:119], v[148:149]
	v_pk_fma_f32 v[120:121], v[140:141], v[120:121], v[154:155]
	v_pk_fma_f32 v[114:115], v[140:141], v[114:115], v[156:157]
	v_pk_fma_f32 v[116:117], v[140:141], v[116:117], v[194:195]
	v_cvt_pk_bf16_f32 v196, v118, v119
	v_cvt_pk_bf16_f32 v197, v120, v121
	v_cvt_pk_bf16_f32 v198, v114, v115
	v_cvt_pk_bf16_f32 v199, v116, v117
	global_store_dwordx4 v146, v[196:199], s[40:41] offset:256
	v_pk_fma_f32 v[178:179], v[118:119], v[118:119], v[178:179]
	v_pk_fma_f32 v[178:179], v[120:121], v[120:121], v[178:179]
	v_pk_fma_f32 v[178:179], v[114:115], v[114:115], v[178:179]
	v_pk_fma_f32 v[178:179], v[116:117], v[116:117], v[178:179]
	v_add_f32_e32 v178, v178, v179
	s_waitcnt vmcnt(14)
	s_add_u32 s40, s62, 0x8000
	s_addc_u32 s41, s63, 0
	v_lshlrev_b32_e32 v148, 16, v186
	v_and_b32_e32 v149, 0xffff0000, v186
	v_lshlrev_b32_e32 v154, 16, v187
	v_and_b32_e32 v155, 0xffff0000, v187
	v_lshlrev_b32_e32 v156, 16, v188
	v_and_b32_e32 v157, 0xffff0000, v188
	v_lshlrev_b32_e32 v194, 16, v189
	v_and_b32_e32 v195, 0xffff0000, v189
	v_pk_fma_f32 v[110:111], v[140:141], v[110:111], v[148:149]
	v_pk_fma_f32 v[112:113], v[140:141], v[112:113], v[154:155]
	v_pk_fma_f32 v[106:107], v[140:141], v[106:107], v[156:157]
	v_pk_fma_f32 v[108:109], v[140:141], v[108:109], v[194:195]
	v_cvt_pk_bf16_f32 v196, v110, v111
	v_cvt_pk_bf16_f32 v197, v112, v113
	v_cvt_pk_bf16_f32 v198, v106, v107
	v_cvt_pk_bf16_f32 v199, v108, v109
	global_store_dwordx4 v146, v[196:199], s[40:41]
	v_pk_mul_f32 v[186:187], v[110:111], v[110:111]
	v_pk_fma_f32 v[186:187], v[112:113], v[112:113], v[186:187]
	v_pk_fma_f32 v[186:187], v[106:107], v[106:107], v[186:187]
	v_pk_fma_f32 v[186:187], v[108:109], v[108:109], v[186:187]
	v_lshlrev_b32_e32 v148, 16, v190
	v_and_b32_e32 v149, 0xffff0000, v190
	v_lshlrev_b32_e32 v154, 16, v191
	v_and_b32_e32 v155, 0xffff0000, v191
	v_lshlrev_b32_e32 v156, 16, v192
	v_and_b32_e32 v157, 0xffff0000, v192
	v_lshlrev_b32_e32 v194, 16, v193
	v_and_b32_e32 v195, 0xffff0000, v193
	v_pk_fma_f32 v[102:103], v[140:141], v[102:103], v[148:149]
	v_pk_fma_f32 v[104:105], v[140:141], v[104:105], v[154:155]
	v_pk_fma_f32 v[98:99], v[140:141], v[98:99], v[156:157]
	v_pk_fma_f32 v[100:101], v[140:141], v[100:101], v[194:195]
	v_cvt_pk_bf16_f32 v196, v102, v103
	v_cvt_pk_bf16_f32 v197, v104, v105
	v_cvt_pk_bf16_f32 v198, v98, v99
	v_cvt_pk_bf16_f32 v199, v100, v101
	global_store_dwordx4 v146, v[196:199], s[40:41] offset:256
	v_pk_fma_f32 v[186:187], v[102:103], v[102:103], v[186:187]
	v_pk_fma_f32 v[186:187], v[104:105], v[104:105], v[186:187]
	v_pk_fma_f32 v[186:187], v[98:99], v[98:99], v[186:187]
	v_pk_fma_f32 v[186:187], v[100:101], v[100:101], v[186:187]
	v_add_f32_e32 v186, v186, v187
	s_waitcnt vmcnt(14)
; __device__ __forceinline__ unsigned pk2(float lo, float hi) { f32x2n v = {lo, hi}; bf16x2n b = __builtin_convertvector(v, bf16x2n); return __builtin_bit_cast(unsigned, b); }
;     __device__ __forceinline__ void operator()(const f32x4 (&acc)[2][2][4][2], const Unit& u, int wr, int wc, int fr, int fq) const {
;     ...
;             for (int m = 0; m < 4; ++m) { const unsigned row = row0 + ai * HALF + m * 16; const unsigned off = row * 1024u + col0; float s = 0.f;
;                 const u32x4 bv0 = *(const u32x4*)(xb + off), bv1 = *(const u32x4*)(xb + off + HALF);
; #pragma unroll
;                 for (int bj = 0; bj < 2; ++bj) { const u32x4 bv = bj ? bv1 : bv0;
;                     const f32x4 b0 = {__uint_as_float(bv.x << 16), __uint_as_float(bv.x & 0xffff0000u), __uint_as_float(bv.y << 16), __uint_as_float(bv.y & 0xffff0000u)};
;                     const f32x4 b1 = {__uint_as_float(bv.z << 16), __uint_as_float(bv.z & 0xffff0000u), __uint_as_float(bv.w << 16), __uint_as_float(bv.w & 0xffff0000u)};
;                     const f32x4 v0 = b0 + acc[ai][bj][m][0] * scale, v1 = b1 + acc[ai][bj][m][1] * scale;
;                     u32x4 w; w.x = pk2(v0[0], v0[1]); w.y = pk2(v0[2], v0[3]); w.z = pk2(v1[0], v1[1]); w.w = pk2(v1[2], v1[3]);
;                     *(u32x4*)(xb + off + bj * HALF) = w;
;                     s += (v0[0] * v0[0] + v0[1] * v0[1]) + (v0[2] * v0[2] + v0[3] * v0[3]) + (v1[0] * v1[0] + v1[1] * v1[1]) + (v1[2] * v1[2] + v1[3] * v1[3]); }
	s_add_u32 s40, s62, 0x10000
	s_addc_u32 s41, s63, 0
	v_lshlrev_b32_e32 v148, 16, v210
	v_and_b32_e32 v149, 0xffff0000, v210
	v_lshlrev_b32_e32 v154, 16, v211
	v_and_b32_e32 v155, 0xffff0000, v211
	v_lshlrev_b32_e32 v156, 16, v212
	v_and_b32_e32 v157, 0xffff0000, v212
	v_lshlrev_b32_e32 v194, 16, v213
	v_and_b32_e32 v195, 0xffff0000, v213
	v_pk_fma_f32 v[94:95], v[140:141], v[94:95], v[148:149]
	v_pk_fma_f32 v[96:97], v[140:141], v[96:97], v[154:155]
	v_pk_fma_f32 v[90:91], v[140:141], v[90:91], v[156:157]
	v_pk_fma_f32 v[92:93], v[140:141], v[92:93], v[194:195]
	v_cvt_pk_bf16_f32 v196, v94, v95
	v_cvt_pk_bf16_f32 v197, v96, v97
	v_cvt_pk_bf16_f32 v198, v90, v91
	v_cvt_pk_bf16_f32 v199, v92, v93
	global_store_dwordx4 v146, v[196:199], s[40:41]
	v_pk_mul_f32 v[210:211], v[94:95], v[94:95]
	v_pk_fma_f32 v[210:211], v[96:97], v[96:97], v[210:211]
	v_pk_fma_f32 v[210:211], v[90:91], v[90:91], v[210:211]
	v_pk_fma_f32 v[210:211], v[92:93], v[92:93], v[210:211]
	v_lshlrev_b32_e32 v148, 16, v214
	v_and_b32_e32 v149, 0xffff0000, v214
	v_lshlrev_b32_e32 v154, 16, v215
	v_and_b32_e32 v155, 0xffff0000, v215
	v_lshlrev_b32_e32 v156, 16, v216
	v_and_b32_e32 v157, 0xffff0000, v216
	v_lshlrev_b32_e32 v194, 16, v217
	v_and_b32_e32 v195, 0xffff0000, v217
	v_pk_fma_f32 v[86:87], v[140:141], v[86:87], v[148:149]
	v_pk_fma_f32 v[88:89], v[140:141], v[88:89], v[154:155]
	v_pk_fma_f32 v[82:83], v[140:141], v[82:83], v[156:157]
	v_pk_fma_f32 v[84:85], v[140:141], v[84:85], v[194:195]
	v_cvt_pk_bf16_f32 v196, v86, v87
	v_cvt_pk_bf16_f32 v197, v88, v89
	v_cvt_pk_bf16_f32 v198, v82, v83
	v_cvt_pk_bf16_f32 v199, v84, v85
	global_store_dwordx4 v146, v[196:199], s[40:41] offset:256
	v_pk_fma_f32 v[210:211], v[86:87], v[86:87], v[210:211]
	v_pk_fma_f32 v[210:211], v[88:89], v[88:89], v[210:211]
	v_pk_fma_f32 v[210:211], v[82:83], v[82:83], v[210:211]
	v_pk_fma_f32 v[210:211], v[84:85], v[84:85], v[210:211]
	v_add_f32_e32 v210, v210, v211
	s_waitcnt vmcnt(14)
	s_add_u32 s40, s62, 0x18000
	s_addc_u32 s41, s63, 0
	v_lshlrev_b32_e32 v148, 16, v218
	v_and_b32_e32 v149, 0xffff0000, v218
	v_lshlrev_b32_e32 v154, 16, v219
	v_and_b32_e32 v155, 0xffff0000, v219
	v_lshlrev_b32_e32 v156, 16, v220
	v_and_b32_e32 v157, 0xffff0000, v220
	v_lshlrev_b32_e32 v194, 16, v221
	v_and_b32_e32 v195, 0xffff0000, v221
	v_pk_fma_f32 v[78:79], v[140:141], v[78:79], v[148:149]
	v_pk_fma_f32 v[80:81], v[140:141], v[80:81], v[154:155]
	v_pk_fma_f32 v[74:75], v[140:141], v[74:75], v[156:157]
	v_pk_fma_f32 v[76:77], v[140:141], v[76:77], v[194:195]
	v_cvt_pk_bf16_f32 v196, v78, v79
	v_cvt_pk_bf16_f32 v197, v80, v81
	v_cvt_pk_bf16_f32 v198, v74, v75
	v_cvt_pk_bf16_f32 v199, v76, v77
	global_store_dwordx4 v146, v[196:199], s[40:41]
	v_pk_mul_f32 v[218:219], v[78:79], v[78:79]
	v_pk_fma_f32 v[218:219], v[80:81], v[80:81], v[218:219]
	v_pk_fma_f32 v[218:219], v[74:75], v[74:75], v[218:219]
	v_pk_fma_f32 v[218:219], v[76:77], v[76:77], v[218:219]
	v_lshlrev_b32_e32 v148, 16, v222
	v_and_b32_e32 v149, 0xffff0000, v222
	v_lshlrev_b32_e32 v154, 16, v223
	v_and_b32_e32 v155, 0xffff0000, v223
	v_lshlrev_b32_e32 v156, 16, v224
	v_and_b32_e32 v157, 0xffff0000, v224
	v_lshlrev_b32_e32 v194, 16, v225
	v_and_b32_e32 v195, 0xffff0000, v225
	v_pk_fma_f32 v[70:71], v[140:141], v[70:71], v[148:149]
	v_pk_fma_f32 v[72:73], v[140:141], v[72:73], v[154:155]
	v_pk_fma_f32 v[66:67], v[140:141], v[66:67], v[156:157]
	v_pk_fma_f32 v[68:69], v[140:141], v[68:69], v[194:195]
	v_cvt_pk_bf16_f32 v196, v70, v71
	v_cvt_pk_bf16_f32 v197, v72, v73
	v_cvt_pk_bf16_f32 v198, v66, v67
	v_cvt_pk_bf16_f32 v199, v68, v69
	global_store_dwordx4 v146, v[196:199], s[40:41] offset:256
	v_pk_fma_f32 v[218:219], v[70:71], v[70:71], v[218:219]
	v_pk_fma_f32 v[218:219], v[72:73], v[72:73], v[218:219]
	v_pk_fma_f32 v[218:219], v[66:67], v[66:67], v[218:219]
	v_pk_fma_f32 v[218:219], v[68:69], v[68:69], v[218:219]
	v_add_f32_e32 v218, v218, v219
	s_waitcnt vmcnt(14)
	s_add_u32 s40, s62, 0x40000
	s_addc_u32 s41, s63, 0
	v_lshlrev_b32_e32 v148, 16, v226
	v_and_b32_e32 v149, 0xffff0000, v226
	v_lshlrev_b32_e32 v154, 16, v227
	v_and_b32_e32 v155, 0xffff0000, v227
	v_lshlrev_b32_e32 v156, 16, v228
	v_and_b32_e32 v157, 0xffff0000, v228
	v_lshlrev_b32_e32 v194, 16, v229
	v_and_b32_e32 v195, 0xffff0000, v229
	v_pk_fma_f32 v[62:63], v[140:141], v[62:63], v[148:149]
	v_pk_fma_f32 v[64:65], v[140:141], v[64:65], v[154:155]
	v_pk_fma_f32 v[58:59], v[140:141], v[58:59], v[156:157]
	v_pk_fma_f32 v[60:61], v[140:141], v[60:61], v[194:195]
	v_cvt_pk_bf16_f32 v196, v62, v63
	v_cvt_pk_bf16_f32 v197, v64, v65
	v_cvt_pk_bf16_f32 v198, v58, v59
	v_cvt_pk_bf16_f32 v199, v60, v61
	global_store_dwordx4 v146, v[196:199], s[40:41]
	v_pk_mul_f32 v[226:227], v[62:63], v[62:63]
	v_pk_fma_f32 v[226:227], v[64:65], v[64:65], v[226:227]
	v_pk_fma_f32 v[226:227], v[58:59], v[58:59], v[226:227]
	v_pk_fma_f32 v[226:227], v[60:61], v[60:61], v[226:227]
	v_lshlrev_b32_e32 v148, 16, v230
	v_and_b32_e32 v149, 0xffff0000, v230
	v_lshlrev_b32_e32 v154, 16, v231
	v_and_b32_e32 v155, 0xffff0000, v231
	v_lshlrev_b32_e32 v156, 16, v232
	v_and_b32_e32 v157, 0xffff0000, v232
	v_lshlrev_b32_e32 v194, 16, v233
	v_and_b32_e32 v195, 0xffff0000, v233
	v_pk_fma_f32 v[54:55], v[140:141], v[54:55], v[148:149]
	v_pk_fma_f32 v[56:57], v[140:141], v[56:57], v[154:155]
	v_pk_fma_f32 v[50:51], v[140:141], v[50:51], v[156:157]
	v_pk_fma_f32 v[52:53], v[140:141], v[52:53], v[194:195]
	v_cvt_pk_bf16_f32 v196, v54, v55
	v_cvt_pk_bf16_f32 v197, v56, v57
	v_cvt_pk_bf16_f32 v198, v50, v51
	v_cvt_pk_bf16_f32 v199, v52, v53
	global_store_dwordx4 v146, v[196:199], s[40:41] offset:256
	v_pk_fma_f32 v[226:227], v[54:55], v[54:55], v[226:227]
	v_pk_fma_f32 v[226:227], v[56:57], v[56:57], v[226:227]
	v_pk_fma_f32 v[226:227], v[50:51], v[50:51], v[226:227]
	v_pk_fma_f32 v[226:227], v[52:53], v[52:53], v[226:227]
	v_add_f32_e32 v226, v226, v227
	s_waitcnt vmcnt(14)
; __device__ __forceinline__ unsigned pk2(float lo, float hi) { f32x2n v = {lo, hi}; bf16x2n b = __builtin_convertvector(v, bf16x2n); return __builtin_bit_cast(unsigned, b); }
;     __device__ __forceinline__ void operator()(const f32x4 (&acc)[2][2][4][2], const Unit& u, int wr, int wc, int fr, int fq) const {
;     ...
;             for (int m = 0; m < 4; ++m) { const unsigned row = row0 + ai * HALF + m * 16; const unsigned off = row * 1024u + col0; float s = 0.f;
;                 const u32x4 bv0 = *(const u32x4*)(xb + off), bv1 = *(const u32x4*)(xb + off + HALF);
; #pragma unroll
;                 for (int bj = 0; bj < 2; ++bj) { const u32x4 bv = bj ? bv1 : bv0;
;                     const f32x4 b0 = {__uint_as_float(bv.x << 16), __uint_as_float(bv.x & 0xffff0000u), __uint_as_float(bv.y << 16), __uint_as_float(bv.y & 0xffff0000u)};
;                     const f32x4 b1 = {__uint_as_float(bv.z << 16), __uint_as_float(bv.z & 0xffff0000u), __uint_as_float(bv.w << 16), __uint_as_float(bv.w & 0xffff0000u)};
;                     const f32x4 v0 = b0 + acc[ai][bj][m][0] * scale, v1 = b1 + acc[ai][bj][m][1] * scale;
;                     u32x4 w; w.x = pk2(v0[0], v0[1]); w.y = pk2(v0[2], v0[3]); w.z = pk2(v1[0], v1[1]); w.w = pk2(v1[2], v1[3]);
;                     *(u32x4*)(xb + off + bj * HALF) = w;
;                     s += (v0[0] * v0[0] + v0[1] * v0[1]) + (v0[2] * v0[2] + v0[3] * v0[3]) + (v1[0] * v1[0] + v1[1] * v1[1]) + (v1[2] * v1[2] + v1[3] * v1[3]); }
	s_add_u32 s40, s62, 0x48000
	s_addc_u32 s41, s63, 0
	v_lshlrev_b32_e32 v148, 16, v234
	v_and_b32_e32 v149, 0xffff0000, v234
	v_lshlrev_b32_e32 v154, 16, v235
	v_and_b32_e32 v155, 0xffff0000, v235
	v_lshlrev_b32_e32 v156, 16, v236
	v_and_b32_e32 v157, 0xffff0000, v236
	v_lshlrev_b32_e32 v194, 16, v237
	v_and_b32_e32 v195, 0xffff0000, v237
	v_pk_fma_f32 v[46:47], v[140:141], v[46:47], v[148:149]
	v_pk_fma_f32 v[48:49], v[140:141], v[48:49], v[154:155]
	v_pk_fma_f32 v[42:43], v[140:141], v[42:43], v[156:157]
	v_pk_fma_f32 v[44:45], v[140:141], v[44:45], v[194:195]
	v_cvt_pk_bf16_f32 v196, v46, v47
	v_cvt_pk_bf16_f32 v197, v48, v49
	v_cvt_pk_bf16_f32 v198, v42, v43
	v_cvt_pk_bf16_f32 v199, v44, v45
	global_store_dwordx4 v146, v[196:199], s[40:41]
	v_pk_mul_f32 v[234:235], v[46:47], v[46:47]
	v_pk_fma_f32 v[234:235], v[48:49], v[48:49], v[234:235]
	v_pk_fma_f32 v[234:235], v[42:43], v[42:43], v[234:235]
	v_pk_fma_f32 v[234:235], v[44:45], v[44:45], v[234:235]
	v_lshlrev_b32_e32 v148, 16, v238
	v_and_b32_e32 v149, 0xffff0000, v238
	v_lshlrev_b32_e32 v154, 16, v239
	v_and_b32_e32 v155, 0xffff0000, v239
	v_lshlrev_b32_e32 v156, 16, v240
	v_and_b32_e32 v157, 0xffff0000, v240
	v_lshlrev_b32_e32 v194, 16, v241
	v_and_b32_e32 v195, 0xffff0000, v241
	v_pk_fma_f32 v[38:39], v[140:141], v[38:39], v[148:149]
	v_pk_fma_f32 v[40:41], v[140:141], v[40:41], v[154:155]
	v_pk_fma_f32 v[34:35], v[140:141], v[34:35], v[156:157]
	v_pk_fma_f32 v[36:37], v[140:141], v[36:37], v[194:195]
	v_cvt_pk_bf16_f32 v196, v38, v39
	v_cvt_pk_bf16_f32 v197, v40, v41
	v_cvt_pk_bf16_f32 v198, v34, v35
	v_cvt_pk_bf16_f32 v199, v36, v37
	global_store_dwordx4 v146, v[196:199], s[40:41] offset:256
	v_pk_fma_f32 v[234:235], v[38:39], v[38:39], v[234:235]
	v_pk_fma_f32 v[234:235], v[40:41], v[40:41], v[234:235]
	v_pk_fma_f32 v[234:235], v[34:35], v[34:35], v[234:235]
	v_pk_fma_f32 v[234:235], v[36:37], v[36:37], v[234:235]
	v_add_f32_e32 v234, v234, v235
	s_waitcnt vmcnt(14)
	s_add_u32 s40, s62, 0x50000
	s_addc_u32 s41, s63, 0
	v_lshlrev_b32_e32 v148, 16, v242
	v_and_b32_e32 v149, 0xffff0000, v242
	v_lshlrev_b32_e32 v154, 16, v243
	v_and_b32_e32 v155, 0xffff0000, v243
	v_lshlrev_b32_e32 v156, 16, v244
	v_and_b32_e32 v157, 0xffff0000, v244
	v_lshlrev_b32_e32 v194, 16, v245
	v_and_b32_e32 v195, 0xffff0000, v245
	v_pk_fma_f32 v[30:31], v[140:141], v[30:31], v[148:149]
	v_pk_fma_f32 v[32:33], v[140:141], v[32:33], v[154:155]
	v_pk_fma_f32 v[26:27], v[140:141], v[26:27], v[156:157]
	v_pk_fma_f32 v[28:29], v[140:141], v[28:29], v[194:195]
	v_cvt_pk_bf16_f32 v196, v30, v31
	v_cvt_pk_bf16_f32 v197, v32, v33
	v_cvt_pk_bf16_f32 v198, v26, v27
	v_cvt_pk_bf16_f32 v199, v28, v29
	global_store_dwordx4 v146, v[196:199], s[40:41]
	v_pk_mul_f32 v[242:243], v[30:31], v[30:31]
	v_pk_fma_f32 v[242:243], v[32:33], v[32:33], v[242:243]
	v_pk_fma_f32 v[242:243], v[26:27], v[26:27], v[242:243]
	v_pk_fma_f32 v[242:243], v[28:29], v[28:29], v[242:243]
	v_lshlrev_b32_e32 v148, 16, v246
	v_and_b32_e32 v149, 0xffff0000, v246
	v_lshlrev_b32_e32 v154, 16, v247
	v_and_b32_e32 v155, 0xffff0000, v247
	v_lshlrev_b32_e32 v156, 16, v248
	v_and_b32_e32 v157, 0xffff0000, v248
	v_lshlrev_b32_e32 v194, 16, v249
	v_and_b32_e32 v195, 0xffff0000, v249
	v_pk_fma_f32 v[22:23], v[140:141], v[22:23], v[148:149]
	v_pk_fma_f32 v[24:25], v[140:141], v[24:25], v[154:155]
	v_pk_fma_f32 v[18:19], v[140:141], v[18:19], v[156:157]
	v_pk_fma_f32 v[20:21], v[140:141], v[20:21], v[194:195]
	v_cvt_pk_bf16_f32 v196, v22, v23
	v_cvt_pk_bf16_f32 v197, v24, v25
	v_cvt_pk_bf16_f32 v198, v18, v19
	v_cvt_pk_bf16_f32 v199, v20, v21
	global_store_dwordx4 v146, v[196:199], s[40:41] offset:256
	v_pk_fma_f32 v[242:243], v[22:23], v[22:23], v[242:243]
	v_pk_fma_f32 v[242:243], v[24:25], v[24:25], v[242:243]
	v_pk_fma_f32 v[242:243], v[18:19], v[18:19], v[242:243]
	v_pk_fma_f32 v[242:243], v[20:21], v[20:21], v[242:243]
	v_add_f32_e32 v242, v242, v243
	s_waitcnt vmcnt(14)
; __device__ __forceinline__ unsigned pk2(float lo, float hi) { f32x2n v = {lo, hi}; bf16x2n b = __builtin_convertvector(v, bf16x2n); return __builtin_bit_cast(unsigned, b); }
;     __device__ __forceinline__ void operator()(const f32x4 (&acc)[2][2][4][2], const Unit& u, int wr, int wc, int fr, int fq) const {
;     ...
;             for (int m = 0; m < 4; ++m) { const unsigned row = row0 + ai * HALF + m * 16; const unsigned off = row * 1024u + col0; float s = 0.f;
;                 const u32x4 bv0 = *(const u32x4*)(xb + off), bv1 = *(const u32x4*)(xb + off + HALF);
; #pragma unroll
;                 for (int bj = 0; bj < 2; ++bj) { const u32x4 bv = bj ? bv1 : bv0;
;                     const f32x4 b0 = {__uint_as_float(bv.x << 16), __uint_as_float(bv.x & 0xffff0000u), __uint_as_float(bv.y << 16), __uint_as_float(bv.y & 0xffff0000u)};
;                     const f32x4 b1 = {__uint_as_float(bv.z << 16), __uint_as_float(bv.z & 0xffff0000u), __uint_as_float(bv.w << 16), __uint_as_float(bv.w & 0xffff0000u)};
;                     const f32x4 v0 = b0 + acc[ai][bj][m][0] * scale, v1 = b1 + acc[ai][bj][m][1] * scale;
;                     u32x4 w; w.x = pk2(v0[0], v0[1]); w.y = pk2(v0[2], v0[3]); w.z = pk2(v1[0], v1[1]); w.w = pk2(v1[2], v1[3]);
;                     *(u32x4*)(xb + off + bj * HALF) = w;
;                     s += (v0[0] * v0[0] + v0[1] * v0[1]) + (v0[2] * v0[2] + v0[3] * v0[3]) + (v1[0] * v1[0] + v1[1] * v1[1]) + (v1[2] * v1[2] + v1[3] * v1[3]); }
;                 s += __shfl_xor(s, 16); s += __shfl_xor(s, 32);
;                 if (fq == 0) ssq_out[(size_t)row * 16 + u.pn * 4 + wc] = s;
;                 asm volatile("" ::: "memory"); }
	s_add_u32 s40, s62, 0x58000
	s_addc_u32 s41, s63, 0
	v_lshlrev_b32_e32 v148, 16, v170
	v_and_b32_e32 v149, 0xffff0000, v170
	v_lshlrev_b32_e32 v154, 16, v171
	v_and_b32_e32 v155, 0xffff0000, v171
	v_lshlrev_b32_e32 v156, 16, v172
	v_and_b32_e32 v157, 0xffff0000, v172
	v_lshlrev_b32_e32 v194, 16, v173
	v_and_b32_e32 v195, 0xffff0000, v173
	v_pk_fma_f32 v[14:15], v[140:141], v[14:15], v[148:149]
	v_pk_fma_f32 v[16:17], v[140:141], v[16:17], v[154:155]
	v_pk_fma_f32 v[10:11], v[140:141], v[10:11], v[156:157]
	v_pk_fma_f32 v[12:13], v[140:141], v[12:13], v[194:195]
	v_cvt_pk_bf16_f32 v196, v14, v15
	v_cvt_pk_bf16_f32 v197, v16, v17
	v_cvt_pk_bf16_f32 v198, v10, v11
	v_cvt_pk_bf16_f32 v199, v12, v13
	global_store_dwordx4 v146, v[196:199], s[40:41]
	v_pk_mul_f32 v[170:171], v[14:15], v[14:15]
	v_pk_fma_f32 v[170:171], v[16:17], v[16:17], v[170:171]
	v_pk_fma_f32 v[170:171], v[10:11], v[10:11], v[170:171]
	v_pk_fma_f32 v[170:171], v[12:13], v[12:13], v[170:171]
	v_lshlrev_b32_e32 v148, 16, v174
	v_and_b32_e32 v149, 0xffff0000, v174
	v_lshlrev_b32_e32 v154, 16, v175
	v_and_b32_e32 v155, 0xffff0000, v175
	v_lshlrev_b32_e32 v156, 16, v176
	v_and_b32_e32 v157, 0xffff0000, v176
	v_lshlrev_b32_e32 v194, 16, v177
	v_and_b32_e32 v195, 0xffff0000, v177
	v_pk_fma_f32 v[4:5], v[140:141], v[4:5], v[148:149]
	v_pk_fma_f32 v[6:7], v[140:141], v[6:7], v[154:155]
	v_pk_fma_f32 v[0:1], v[140:141], v[0:1], v[156:157]
	v_pk_fma_f32 v[2:3], v[140:141], v[2:3], v[194:195]
	v_cvt_pk_bf16_f32 v196, v4, v5
	v_cvt_pk_bf16_f32 v197, v6, v7
	v_cvt_pk_bf16_f32 v198, v0, v1
	v_cvt_pk_bf16_f32 v199, v2, v3
	global_store_dwordx4 v146, v[196:199], s[40:41] offset:256
	v_pk_fma_f32 v[170:171], v[4:5], v[4:5], v[170:171]
	v_pk_fma_f32 v[170:171], v[6:7], v[6:7], v[170:171]
	v_pk_fma_f32 v[170:171], v[0:1], v[0:1], v[170:171]
	v_pk_fma_f32 v[170:171], v[2:3], v[2:3], v[170:171]
	v_add_f32_e32 v170, v170, v171
	ds_bpermute_b32 v179, v153, v178
	ds_bpermute_b32 v187, v153, v186
	ds_bpermute_b32 v211, v153, v210
	ds_bpermute_b32 v219, v153, v218
	ds_bpermute_b32 v227, v153, v226
	ds_bpermute_b32 v235, v153, v234
	ds_bpermute_b32 v243, v153, v242
	ds_bpermute_b32 v171, v153, v170
	s_waitcnt lgkmcnt(0)
	v_add_f32_e32 v178, v178, v179
	v_add_f32_e32 v186, v186, v187
	v_add_f32_e32 v210, v210, v211
	v_add_f32_e32 v218, v218, v219
	v_add_f32_e32 v226, v226, v227
	v_add_f32_e32 v234, v234, v235
	v_add_f32_e32 v242, v242, v243
	v_add_f32_e32 v170, v170, v171
	ds_bpermute_b32 v179, v139, v178
	ds_bpermute_b32 v187, v139, v186
	ds_bpermute_b32 v211, v139, v210
	ds_bpermute_b32 v219, v139, v218
	ds_bpermute_b32 v227, v139, v226
	ds_bpermute_b32 v235, v139, v234
	ds_bpermute_b32 v243, v139, v242
	ds_bpermute_b32 v171, v139, v170
	s_waitcnt lgkmcnt(0)
	v_add_f32_e32 v178, v178, v179
	v_add_f32_e32 v186, v186, v187
	v_add_f32_e32 v210, v210, v211
	v_add_f32_e32 v218, v218, v219
	v_add_f32_e32 v226, v226, v227
	v_add_f32_e32 v234, v234, v235
	v_add_f32_e32 v242, v242, v243
	v_add_f32_e32 v170, v170, v171
	v_and_b32_e32 v148, 15, v202
	v_lshlrev_b32_e32 v148, 4, v148
	s_cmp_eq_u64 s[18:19], 0
	s_cselect_b32 s24, 0x800, 0
	s_lshl_b32 s38, s81, 2
	s_add_i32 s24, s24, s38
	s_add_i32 s24, s24, 0x20100
	v_add_u32_e32 v148, s24, v148
	s_and_saveexec_b64 s[40:41], s[8:9]
	ds_write_b32 v148, v178
	ds_write_b32 v148, v186 offset:256
	ds_write_b32 v148, v210 offset:512
	ds_write_b32 v148, v218 offset:768
	ds_write_b32 v148, v226 offset:1024
	ds_write_b32 v148, v234 offset:1280
	ds_write_b32 v148, v242 offset:1536
	ds_write_b32 v148, v170 offset:1792
	s_or_b64 exec, exec, s[40:41]
	s_waitcnt lgkmcnt(0)
	s_barrier
	s_cmp_eq_u64 s[18:19], 0
	s_cbranch_scc1 .Lres_ssq_done
	v_lshlrev_b32_e32 v148, 4, v202
	s_lshl_b32 s24, s81, 10
	s_add_i32 s24, s24, 0x20100
	v_add_u32_e32 v148, s24, v148
	ds_read_b128 v[154:157], v148
	s_lshr_b32 s24, s81, 1
	s_lshl_b32 s24, s24, 6
	s_and_b32 s38, s81, 1
	s_lshl_b32 s38, s38, 7
	s_or_b32 s24, s24, s38
	s_lshl_b32 s24, s24, 6
	s_lshl_b32 s38, s96, 14
	s_add_i32 s24, s24, s38
	s_lshl_b32 s38, s56, 4
	s_add_i32 s24, s24, s38
	s_add_u32 s24, s16, s24
	s_addc_u32 s25, s17, 0
	v_lshlrev_b32_e32 v149, 6, v202
	s_waitcnt lgkmcnt(0)
	global_store_dwordx4 v149, v[154:157], s[24:25]
.Lres_ssq_done:
	s_and_b64 vcc, exec, s[10:11]
	s_mov_b64 s[10:11], -1
	s_cbranch_vccnz .LBB0_639
	s_andn2_b64 vcc, exec, s[14:15]
	s_cbranch_vccnz .LBB0_638
	s_barrier
	s_branch .LBB0_638

; __global__ void __launch_bounds__(NTHR, 2) hymba_fwd(Args a) {
;     ...
;     { const float* fn = a.in[20]; const float* sq = ssq + (size_t)12 * M * 16;
;       for (int m = gw; m < M; m += NGW) { const float rs = pg8::row_rs(sq, (unsigned)m);
;           const u32x4* xr = (const u32x4*)(XB + (size_t)m * D); f32x4* orow = (f32x4*)(out + (size_t)m * D);
; #pragma unroll
;           for (int hlf = 0; hlf < 2; ++hlf) { const u32x4 bv = xr[64 * hlf + lane]; const f32x4 w0 = ((const f32x4*)fn)[2 * (64 * hlf + lane)], w1 = ((const f32x4*)fn)[2 * (64 * hlf + lane) + 1];
;               const f32x4 b0 = {__uint_as_float(bv.x << 16), __uint_as_float(bv.x & 0xffff0000u), __uint_as_float(bv.y << 16), __uint_as_float(bv.y & 0xffff0000u)};
;               const f32x4 b1 = {__uint_as_float(bv.z << 16), __uint_as_float(bv.z & 0xffff0000u), __uint_as_float(bv.w << 16), __uint_as_float(bv.w & 0xffff0000u)};
;               orow[2 * (64 * hlf + lane)] = b0 * rs * w0; orow[2 * (64 * hlf + lane) + 1] = b1 * rs * w1; } } }
.Lfin_batch:
	s_mov_b32 s14, s34
	s_lshl_b32 s10, s14, 11
	s_add_u32 s10, s2, s10
	s_addc_u32 s11, s3, 0
	global_load_dwordx4 v[10:13], v2, s[10:11] nt
	global_load_dwordx4 v[14:17], v2, s[10:11] offset:1024 nt
	s_lshl_b32 s10, s14, 6
	s_add_u32 s10, s4, s10
	s_addc_u32 s11, s5, 0
	global_load_dwordx4 v[18:21], v1, s[10:11]
	global_load_dwordx4 v[22:25], v1, s[10:11] offset:16
	global_load_dwordx4 v[26:29], v1, s[10:11] offset:32
	global_load_dwordx4 v[30:33], v1, s[10:11] offset:48
	s_add_i32 s14, s14, s8
	s_lshl_b32 s10, s14, 11
	s_add_u32 s10, s2, s10
	s_addc_u32 s11, s3, 0
	global_load_dwordx4 v[34:37], v2, s[10:11] nt
	global_load_dwordx4 v[38:41], v2, s[10:11] offset:1024 nt
	s_lshl_b32 s10, s14, 6
	s_add_u32 s10, s4, s10
	s_addc_u32 s11, s5, 0
	global_load_dwordx4 v[42:45], v1, s[10:11]
	global_load_dwordx4 v[46:49], v1, s[10:11] offset:16
	global_load_dwordx4 v[50:53], v1, s[10:11] offset:32
	global_load_dwordx4 v[54:57], v1, s[10:11] offset:48
	s_add_i32 s14, s14, s8
	s_lshl_b32 s10, s14, 11
	s_add_u32 s10, s2, s10
	s_addc_u32 s11, s3, 0
	global_load_dwordx4 v[58:61], v2, s[10:11] nt
	global_load_dwordx4 v[62:65], v2, s[10:11] offset:1024 nt
	s_lshl_b32 s10, s14, 6
	s_add_u32 s10, s4, s10
	s_addc_u32 s11, s5, 0
	global_load_dwordx4 v[66:69], v1, s[10:11]
	global_load_dwordx4 v[70:73], v1, s[10:11] offset:16
	global_load_dwordx4 v[74:77], v1, s[10:11] offset:32
	global_load_dwordx4 v[78:81], v1, s[10:11] offset:48
	s_add_i32 s14, s14, s8
	s_lshl_b32 s10, s14, 11
	s_add_u32 s10, s2, s10
	s_addc_u32 s11, s3, 0
	global_load_dwordx4 v[82:85], v2, s[10:11] nt
	global_load_dwordx4 v[86:89], v2, s[10:11] offset:1024 nt
	s_lshl_b32 s10, s14, 6
	s_add_u32 s10, s4, s10
	s_addc_u32 s11, s5, 0
	global_load_dwordx4 v[90:93], v1, s[10:11]
	global_load_dwordx4 v[94:97], v1, s[10:11] offset:16
	global_load_dwordx4 v[98:101], v1, s[10:11] offset:32
	global_load_dwordx4 v[102:105], v1, s[10:11] offset:48
	s_mov_b32 s14, s34
	s_waitcnt vmcnt(18)
	v_pk_add_f32 v[18:19], v[18:19], v[22:23]
	v_pk_add_f32 v[20:21], v[20:21], v[24:25]
	v_pk_add_f32 v[26:27], v[26:27], v[30:31]
	v_pk_add_f32 v[28:29], v[28:29], v[32:33]
	v_pk_add_f32 v[18:19], v[18:19], v[26:27]
	v_pk_add_f32 v[20:21], v[20:21], v[28:29]
	v_add_f32_e32 v18, v18, v19
	v_add_f32_e32 v20, v20, v21
	v_add_f32_e32 v18, v18, v20
	v_fmamk_f32 v18, v18, 0x3a800000, v0
	v_rsq_f32_e32 v18, v18
	s_lshl_b32 s10, s14, 12
	s_add_u32 s10, s28, s10
	s_addc_u32 s11, s29, 0
	v_lshlrev_b32_e32 v144, 16, v10
	v_and_b32_e32 v145, 0xffff0000, v10
	v_lshlrev_b32_e32 v146, 16, v11
	v_and_b32_e32 v147, 0xffff0000, v11
	v_lshlrev_b32_e32 v148, 16, v12
	v_and_b32_e32 v149, 0xffff0000, v12
	v_lshlrev_b32_e32 v150, 16, v13
	v_and_b32_e32 v151, 0xffff0000, v13
	v_pk_mul_f32 v[144:145], v[18:19], v[144:145] op_sel_hi:[0,1]
	v_pk_mul_f32 v[146:147], v[18:19], v[146:147] op_sel_hi:[0,1]
	v_pk_mul_f32 v[148:149], v[18:19], v[148:149] op_sel_hi:[0,1]
	v_pk_mul_f32 v[150:151], v[18:19], v[150:151] op_sel_hi:[0,1]
	v_pk_mul_f32 v[144:145], v[128:129], v[144:145]
	v_pk_mul_f32 v[146:147], v[130:131], v[146:147]
	v_pk_mul_f32 v[148:149], v[132:133], v[148:149]
	v_pk_mul_f32 v[150:151], v[134:135], v[150:151]
	global_store_dwordx4 v3, v[144:147], s[10:11] nt
	global_store_dwordx4 v3, v[148:151], s[10:11] offset:16 nt
	v_lshlrev_b32_e32 v152, 16, v14
	v_and_b32_e32 v153, 0xffff0000, v14
	v_lshlrev_b32_e32 v154, 16, v15
	v_and_b32_e32 v155, 0xffff0000, v15
	v_lshlrev_b32_e32 v156, 16, v16
	v_and_b32_e32 v157, 0xffff0000, v16
	v_lshlrev_b32_e32 v158, 16, v17
	v_and_b32_e32 v159, 0xffff0000, v17
	v_pk_mul_f32 v[152:153], v[18:19], v[152:153] op_sel_hi:[0,1]
	v_pk_mul_f32 v[154:155], v[18:19], v[154:155] op_sel_hi:[0,1]
	v_pk_mul_f32 v[156:157], v[18:19], v[156:157] op_sel_hi:[0,1]
	v_pk_mul_f32 v[158:159], v[18:19], v[158:159] op_sel_hi:[0,1]
	v_pk_mul_f32 v[152:153], v[136:137], v[152:153]
	v_pk_mul_f32 v[154:155], v[138:139], v[154:155]
	v_pk_mul_f32 v[156:157], v[140:141], v[156:157]
	v_pk_mul_f32 v[158:159], v[142:143], v[158:159]
	global_store_dwordx4 v3, v[152:155], s[10:11] offset:2048 nt
	global_store_dwordx4 v3, v[156:159], s[10:11] offset:2064 nt
	s_add_i32 s14, s14, s8
	s_waitcnt vmcnt(16)
	v_pk_add_f32 v[42:43], v[42:43], v[46:47]
	v_pk_add_f32 v[44:45], v[44:45], v[48:49]
	v_pk_add_f32 v[50:51], v[50:51], v[54:55]
	v_pk_add_f32 v[52:53], v[52:53], v[56:57]
	v_pk_add_f32 v[42:43], v[42:43], v[50:51]
	v_pk_add_f32 v[44:45], v[44:45], v[52:53]
	v_add_f32_e32 v42, v42, v43
	v_add_f32_e32 v44, v44, v45
	v_add_f32_e32 v42, v42, v44
	v_fmamk_f32 v42, v42, 0x3a800000, v0
	v_rsq_f32_e32 v42, v42
	s_lshl_b32 s10, s14, 12
	s_add_u32 s10, s28, s10
	s_addc_u32 s11, s29, 0
	v_lshlrev_b32_e32 v144, 16, v34
	v_and_b32_e32 v145, 0xffff0000, v34
	v_lshlrev_b32_e32 v146, 16, v35
	v_and_b32_e32 v147, 0xffff0000, v35
	v_lshlrev_b32_e32 v148, 16, v36
	v_and_b32_e32 v149, 0xffff0000, v36
	v_lshlrev_b32_e32 v150, 16, v37
	v_and_b32_e32 v151, 0xffff0000, v37
	v_pk_mul_f32 v[144:145], v[42:43], v[144:145] op_sel_hi:[0,1]
	v_pk_mul_f32 v[146:147], v[42:43], v[146:147] op_sel_hi:[0,1]
	v_pk_mul_f32 v[148:149], v[42:43], v[148:149] op_sel_hi:[0,1]
	v_pk_mul_f32 v[150:151], v[42:43], v[150:151] op_sel_hi:[0,1]
	v_pk_mul_f32 v[144:145], v[128:129], v[144:145]
	v_pk_mul_f32 v[146:147], v[130:131], v[146:147]
	v_pk_mul_f32 v[148:149], v[132:133], v[148:149]
	v_pk_mul_f32 v[150:151], v[134:135], v[150:151]
	global_store_dwordx4 v3, v[144:147], s[10:11] nt
	global_store_dwordx4 v3, v[148:151], s[10:11] offset:16 nt
	v_lshlrev_b32_e32 v152, 16, v38
	v_and_b32_e32 v153, 0xffff0000, v38
	v_lshlrev_b32_e32 v154, 16, v39
	v_and_b32_e32 v155, 0xffff0000, v39
	v_lshlrev_b32_e32 v156, 16, v40
	v_and_b32_e32 v157, 0xffff0000, v40
	v_lshlrev_b32_e32 v158, 16, v41
	v_and_b32_e32 v159, 0xffff0000, v41
	v_pk_mul_f32 v[152:153], v[42:43], v[152:153] op_sel_hi:[0,1]
	v_pk_mul_f32 v[154:155], v[42:43], v[154:155] op_sel_hi:[0,1]
	v_pk_mul_f32 v[156:157], v[42:43], v[156:157] op_sel_hi:[0,1]
	v_pk_mul_f32 v[158:159], v[42:43], v[158:159] op_sel_hi:[0,1]
	v_pk_mul_f32 v[152:153], v[136:137], v[152:153]
	v_pk_mul_f32 v[154:155], v[138:139], v[154:155]
	v_pk_mul_f32 v[156:157], v[140:141], v[156:157]
	v_pk_mul_f32 v[158:159], v[142:143], v[158:159]
	global_store_dwordx4 v3, v[152:155], s[10:11] offset:2048 nt
	global_store_dwordx4 v3, v[156:159], s[10:11] offset:2064 nt
	s_add_i32 s14, s14, s8
	s_waitcnt vmcnt(14)
; __global__ void __launch_bounds__(NTHR, 2) hymba_fwd(Args a) {
;     ...
;     { const float* fn = a.in[20]; const float* sq = ssq + (size_t)12 * M * 16;
;       for (int m = gw; m < M; m += NGW) { const float rs = pg8::row_rs(sq, (unsigned)m);
;           const u32x4* xr = (const u32x4*)(XB + (size_t)m * D); f32x4* orow = (f32x4*)(out + (size_t)m * D);
; #pragma unroll
;           for (int hlf = 0; hlf < 2; ++hlf) { const u32x4 bv = xr[64 * hlf + lane]; const f32x4 w0 = ((const f32x4*)fn)[2 * (64 * hlf + lane)], w1 = ((const f32x4*)fn)[2 * (64 * hlf + lane) + 1];
;               const f32x4 b0 = {__uint_as_float(bv.x << 16), __uint_as_float(bv.x & 0xffff0000u), __uint_as_float(bv.y << 16), __uint_as_float(bv.y & 0xffff0000u)};
;               const f32x4 b1 = {__uint_as_float(bv.z << 16), __uint_as_float(bv.z & 0xffff0000u), __uint_as_float(bv.w << 16), __uint_as_float(bv.w & 0xffff0000u)};
;               orow[2 * (64 * hlf + lane)] = b0 * rs * w0; orow[2 * (64 * hlf + lane) + 1] = b1 * rs * w1; } } }
	v_pk_add_f32 v[66:67], v[66:67], v[70:71]
	v_pk_add_f32 v[68:69], v[68:69], v[72:73]
	v_pk_add_f32 v[74:75], v[74:75], v[78:79]
	v_pk_add_f32 v[76:77], v[76:77], v[80:81]
	v_pk_add_f32 v[66:67], v[66:67], v[74:75]
	v_pk_add_f32 v[68:69], v[68:69], v[76:77]
	v_add_f32_e32 v66, v66, v67
	v_add_f32_e32 v68, v68, v69
	v_add_f32_e32 v66, v66, v68
	v_fmamk_f32 v66, v66, 0x3a800000, v0
	v_rsq_f32_e32 v66, v66
	s_lshl_b32 s10, s14, 12
	s_add_u32 s10, s28, s10
	s_addc_u32 s11, s29, 0
	v_lshlrev_b32_e32 v144, 16, v58
	v_and_b32_e32 v145, 0xffff0000, v58
	v_lshlrev_b32_e32 v146, 16, v59
	v_and_b32_e32 v147, 0xffff0000, v59
	v_lshlrev_b32_e32 v148, 16, v60
	v_and_b32_e32 v149, 0xffff0000, v60
	v_lshlrev_b32_e32 v150, 16, v61
	v_and_b32_e32 v151, 0xffff0000, v61
	v_pk_mul_f32 v[144:145], v[66:67], v[144:145] op_sel_hi:[0,1]
	v_pk_mul_f32 v[146:147], v[66:67], v[146:147] op_sel_hi:[0,1]
	v_pk_mul_f32 v[148:149], v[66:67], v[148:149] op_sel_hi:[0,1]
	v_pk_mul_f32 v[150:151], v[66:67], v[150:151] op_sel_hi:[0,1]
	v_pk_mul_f32 v[144:145], v[128:129], v[144:145]
	v_pk_mul_f32 v[146:147], v[130:131], v[146:147]
	v_pk_mul_f32 v[148:149], v[132:133], v[148:149]
	v_pk_mul_f32 v[150:151], v[134:135], v[150:151]
	global_store_dwordx4 v3, v[144:147], s[10:11] nt
	global_store_dwordx4 v3, v[148:151], s[10:11] offset:16 nt
	v_lshlrev_b32_e32 v152, 16, v62
	v_and_b32_e32 v153, 0xffff0000, v62
	v_lshlrev_b32_e32 v154, 16, v63
	v_and_b32_e32 v155, 0xffff0000, v63
	v_lshlrev_b32_e32 v156, 16, v64
	v_and_b32_e32 v157, 0xffff0000, v64
	v_lshlrev_b32_e32 v158, 16, v65
	v_and_b32_e32 v159, 0xffff0000, v65
	v_pk_mul_f32 v[152:153], v[66:67], v[152:153] op_sel_hi:[0,1]
	v_pk_mul_f32 v[154:155], v[66:67], v[154:155] op_sel_hi:[0,1]
	v_pk_mul_f32 v[156:157], v[66:67], v[156:157] op_sel_hi:[0,1]
	v_pk_mul_f32 v[158:159], v[66:67], v[158:159] op_sel_hi:[0,1]
	v_pk_mul_f32 v[152:153], v[136:137], v[152:153]
	v_pk_mul_f32 v[154:155], v[138:139], v[154:155]
	v_pk_mul_f32 v[156:157], v[140:141], v[156:157]
	v_pk_mul_f32 v[158:159], v[142:143], v[158:159]
	global_store_dwordx4 v3, v[152:155], s[10:11] offset:2048 nt
	global_store_dwordx4 v3, v[156:159], s[10:11] offset:2064 nt
	s_add_i32 s14, s14, s8
	s_waitcnt vmcnt(12)
	v_pk_add_f32 v[90:91], v[90:91], v[94:95]
	v_pk_add_f32 v[92:93], v[92:93], v[96:97]
	v_pk_add_f32 v[98:99], v[98:99], v[102:103]
	v_pk_add_f32 v[100:101], v[100:101], v[104:105]
	v_pk_add_f32 v[90:91], v[90:91], v[98:99]
	v_pk_add_f32 v[92:93], v[92:93], v[100:101]
	v_add_f32_e32 v90, v90, v91
	v_add_f32_e32 v92, v92, v93
	v_add_f32_e32 v90, v90, v92
	v_fmamk_f32 v90, v90, 0x3a800000, v0
	v_rsq_f32_e32 v90, v90
	s_lshl_b32 s10, s14, 12
	s_add_u32 s10, s28, s10
	s_addc_u32 s11, s29, 0
	v_lshlrev_b32_e32 v144, 16, v82
	v_and_b32_e32 v145, 0xffff0000, v82
	v_lshlrev_b32_e32 v146, 16, v83
	v_and_b32_e32 v147, 0xffff0000, v83
	v_lshlrev_b32_e32 v148, 16, v84
	v_and_b32_e32 v149, 0xffff0000, v84
	v_lshlrev_b32_e32 v150, 16, v85
	v_and_b32_e32 v151, 0xffff0000, v85
	v_pk_mul_f32 v[144:145], v[90:91], v[144:145] op_sel_hi:[0,1]
	v_pk_mul_f32 v[146:147], v[90:91], v[146:147] op_sel_hi:[0,1]
	v_pk_mul_f32 v[148:149], v[90:91], v[148:149] op_sel_hi:[0,1]
	v_pk_mul_f32 v[150:151], v[90:91], v[150:151] op_sel_hi:[0,1]
	v_pk_mul_f32 v[144:145], v[128:129], v[144:145]
	v_pk_mul_f32 v[146:147], v[130:131], v[146:147]
	v_pk_mul_f32 v[148:149], v[132:133], v[148:149]
	v_pk_mul_f32 v[150:151], v[134:135], v[150:151]
	global_store_dwordx4 v3, v[144:147], s[10:11] nt
	global_store_dwordx4 v3, v[148:151], s[10:11] offset:16 nt
	v_lshlrev_b32_e32 v152, 16, v86
	v_and_b32_e32 v153, 0xffff0000, v86
	v_lshlrev_b32_e32 v154, 16, v87
	v_and_b32_e32 v155, 0xffff0000, v87
	v_lshlrev_b32_e32 v156, 16, v88
	v_and_b32_e32 v157, 0xffff0000, v88
	v_lshlrev_b32_e32 v158, 16, v89
	v_and_b32_e32 v159, 0xffff0000, v89
	v_pk_mul_f32 v[152:153], v[90:91], v[152:153] op_sel_hi:[0,1]
	v_pk_mul_f32 v[154:155], v[90:91], v[154:155] op_sel_hi:[0,1]
	v_pk_mul_f32 v[156:157], v[90:91], v[156:157] op_sel_hi:[0,1]
	v_pk_mul_f32 v[158:159], v[90:91], v[158:159] op_sel_hi:[0,1]
	v_pk_mul_f32 v[152:153], v[136:137], v[152:153]
	v_pk_mul_f32 v[154:155], v[138:139], v[154:155]
	v_pk_mul_f32 v[156:157], v[140:141], v[156:157]
	v_pk_mul_f32 v[158:159], v[142:143], v[158:159]
	global_store_dwordx4 v3, v[152:155], s[10:11] offset:2048 nt
	global_store_dwordx4 v3, v[156:159], s[10:11] offset:2064 nt
	s_add_i32 s34, s34, s13
	s_add_i32 s12, s34, s9
	s_cmp_gt_i32 s12, 0xffff
	s_cbranch_scc0 .Lfin_batch

; __global__ void __launch_bounds__(NTHR, 2) hymba_fwd(Args a) {
;     ...
;     { const float* fn = a.in[20]; const float* sq = ssq + (size_t)12 * M * 16;
;       for (int m = gw; m < M; m += NGW) { const float rs = pg8::row_rs(sq, (unsigned)m);
;           const u32x4* xr = (const u32x4*)(XB + (size_t)m * D); f32x4* orow = (f32x4*)(out + (size_t)m * D);
; #pragma unroll
;           for (int hlf = 0; hlf < 2; ++hlf) { const u32x4 bv = xr[64 * hlf + lane]; const f32x4 w0 = ((const f32x4*)fn)[2 * (64 * hlf + lane)], w1 = ((const f32x4*)fn)[2 * (64 * hlf + lane) + 1];
;               const f32x4 b0 = {__uint_as_float(bv.x << 16), __uint_as_float(bv.x & 0xffff0000u), __uint_as_float(bv.y << 16), __uint_as_float(bv.y & 0xffff0000u)};
;               const f32x4 b1 = {__uint_as_float(bv.z << 16), __uint_as_float(bv.z & 0xffff0000u), __uint_as_float(bv.w << 16), __uint_as_float(bv.w & 0xffff0000u)};
;               orow[2 * (64 * hlf + lane)] = b0 * rs * w0; orow[2 * (64 * hlf + lane) + 1] = b1 * rs * w1; } } }
.Lfin_one:
	s_lshl_b32 s10, s34, 11
	s_add_u32 s10, s2, s10
	s_addc_u32 s11, s3, 0
	global_load_dwordx4 v[10:13], v2, s[10:11] nt
	global_load_dwordx4 v[14:17], v2, s[10:11] offset:1024 nt
	s_lshl_b32 s10, s34, 6
	s_add_u32 s10, s4, s10
	s_addc_u32 s11, s5, 0
	global_load_dwordx4 v[18:21], v1, s[10:11]
	global_load_dwordx4 v[22:25], v1, s[10:11] offset:16
	global_load_dwordx4 v[26:29], v1, s[10:11] offset:32
	global_load_dwordx4 v[30:33], v1, s[10:11] offset:48
	s_waitcnt vmcnt(0)
	v_pk_add_f32 v[18:19], v[18:19], v[22:23]
	v_pk_add_f32 v[20:21], v[20:21], v[24:25]
	v_pk_add_f32 v[26:27], v[26:27], v[30:31]
	v_pk_add_f32 v[28:29], v[28:29], v[32:33]
	v_pk_add_f32 v[18:19], v[18:19], v[26:27]
	v_pk_add_f32 v[20:21], v[20:21], v[28:29]
	v_add_f32_e32 v18, v18, v19
	v_add_f32_e32 v20, v20, v21
	v_add_f32_e32 v18, v18, v20
	v_fmamk_f32 v18, v18, 0x3a800000, v0
	v_rsq_f32_e32 v18, v18
	s_lshl_b32 s10, s34, 12
	s_add_u32 s10, s28, s10
	s_addc_u32 s11, s29, 0
	v_lshlrev_b32_e32 v144, 16, v10
	v_and_b32_e32 v145, 0xffff0000, v10
	v_lshlrev_b32_e32 v146, 16, v11
	v_and_b32_e32 v147, 0xffff0000, v11
	v_lshlrev_b32_e32 v148, 16, v12
	v_and_b32_e32 v149, 0xffff0000, v12
	v_lshlrev_b32_e32 v150, 16, v13
	v_and_b32_e32 v151, 0xffff0000, v13
	v_pk_mul_f32 v[144:145], v[18:19], v[144:145] op_sel_hi:[0,1]
	v_pk_mul_f32 v[146:147], v[18:19], v[146:147] op_sel_hi:[0,1]
	v_pk_mul_f32 v[148:149], v[18:19], v[148:149] op_sel_hi:[0,1]
	v_pk_mul_f32 v[150:151], v[18:19], v[150:151] op_sel_hi:[0,1]
	v_pk_mul_f32 v[144:145], v[128:129], v[144:145]
	v_pk_mul_f32 v[146:147], v[130:131], v[146:147]
	v_pk_mul_f32 v[148:149], v[132:133], v[148:149]
	v_pk_mul_f32 v[150:151], v[134:135], v[150:151]
	global_store_dwordx4 v3, v[144:147], s[10:11] nt
	global_store_dwordx4 v3, v[148:151], s[10:11] offset:16 nt
	v_lshlrev_b32_e32 v152, 16, v14
	v_and_b32_e32 v153, 0xffff0000, v14
	v_lshlrev_b32_e32 v154, 16, v15
	v_and_b32_e32 v155, 0xffff0000, v15
	v_lshlrev_b32_e32 v156, 16, v16
	v_and_b32_e32 v157, 0xffff0000, v16
	v_lshlrev_b32_e32 v158, 16, v17
	v_and_b32_e32 v159, 0xffff0000, v17
	v_pk_mul_f32 v[152:153], v[18:19], v[152:153] op_sel_hi:[0,1]
	v_pk_mul_f32 v[154:155], v[18:19], v[154:155] op_sel_hi:[0,1]
	v_pk_mul_f32 v[156:157], v[18:19], v[156:157] op_sel_hi:[0,1]
	v_pk_mul_f32 v[158:159], v[18:19], v[158:159] op_sel_hi:[0,1]
	v_pk_mul_f32 v[152:153], v[136:137], v[152:153]
	v_pk_mul_f32 v[154:155], v[138:139], v[154:155]
	v_pk_mul_f32 v[156:157], v[140:141], v[156:157]
	v_pk_mul_f32 v[158:159], v[142:143], v[158:159]
	global_store_dwordx4 v3, v[152:155], s[10:11] offset:2048 nt
	global_store_dwordx4 v3, v[156:159], s[10:11] offset:2064 nt
	s_add_i32 s34, s34, s8
	s_cmp_gt_i32 s34, 0xffff
	s_cbranch_scc0 .Lfin_one
